# K-loop heads aligned to 64 bytes (s_nop fill before the loop label)
# baseline (speedup 1.0000x reference)
.LBB0_340:
	s_ashr_i32 s25, s24, 31
	s_lshl_b64 s[26:27], s[24:25], 19
	s_add_u32 s26, s53, s26
	s_addc_u32 s27, s55, s27
	s_and_b64 s[28:29], s[4:5], exec
	s_cselect_b32 s25, s27, s35
	s_cselect_b32 s31, s26, s34
	s_ashr_i32 s23, s22, 31
	s_lshl_b64 s[28:29], s[22:23], 19
	s_add_u32 s28, s66, s28
	s_addc_u32 s29, s67, s29
	s_and_b64 s[38:39], s[4:5], exec
	s_cselect_b32 s23, s29, s37
	s_cselect_b32 s40, s28, s36
	s_add_u32 s34, s34, 0x40080
	s_addc_u32 s35, s35, 0
	s_add_u32 s77, s36, 0x100
	v_mov_b32_e32 v2, 0
	s_addc_u32 s78, s37, 0
	s_mov_b32 s79, -2
	v_mov_b32_e32 v3, v2
	v_mov_b32_e32 v4, v2
	v_mov_b32_e32 v5, v2
	v_mov_b32_e32 v10, v2
	v_mov_b32_e32 v11, v2
	v_mov_b32_e32 v12, v2
	v_mov_b32_e32 v13, v2
	s_waitcnt vmcnt(0)
	v_mov_b32_e32 v18, v2
	s_waitcnt lgkmcnt(0)
	v_mov_b32_e32 v19, v2
	v_mov_b32_e32 v20, v2
	v_mov_b32_e32 v21, v2
	v_mov_b32_e32 v26, v2
	v_mov_b32_e32 v27, v2
	v_mov_b32_e32 v28, v2
	v_mov_b32_e32 v29, v2
	v_mov_b32_e32 v34, v2
	v_mov_b32_e32 v35, v2
	v_mov_b32_e32 v36, v2
	v_mov_b32_e32 v37, v2
	v_mov_b32_e32 v42, v2
	v_mov_b32_e32 v43, v2
	v_mov_b32_e32 v44, v2
	v_mov_b32_e32 v45, v2
	v_mov_b32_e32 v50, v2
	v_mov_b32_e32 v51, v2
	v_mov_b32_e32 v52, v2
	v_mov_b32_e32 v53, v2
	v_mov_b32_e32 v58, v2
	v_mov_b32_e32 v59, v2
	v_mov_b32_e32 v60, v2
	v_mov_b32_e32 v61, v2
	v_mov_b32_e32 v6, v2
	v_mov_b32_e32 v7, v2
	v_mov_b32_e32 v8, v2
	v_mov_b32_e32 v9, v2
	v_mov_b32_e32 v14, v2
	v_mov_b32_e32 v15, v2
	v_mov_b32_e32 v16, v2
	v_mov_b32_e32 v17, v2
	v_mov_b32_e32 v22, v2
	v_mov_b32_e32 v23, v2
	v_mov_b32_e32 v24, v2
	v_mov_b32_e32 v25, v2
	v_mov_b32_e32 v30, v2
	v_mov_b32_e32 v31, v2
	v_mov_b32_e32 v32, v2
	v_mov_b32_e32 v33, v2
	v_mov_b32_e32 v38, v2
	v_mov_b32_e32 v39, v2
	v_mov_b32_e32 v40, v2
	v_mov_b32_e32 v41, v2
	v_mov_b32_e32 v46, v2
	v_mov_b32_e32 v47, v2
	v_mov_b32_e32 v48, v2
	v_mov_b32_e32 v49, v2
	v_mov_b32_e32 v54, v2
	v_mov_b32_e32 v55, v2
	v_mov_b32_e32 v56, v2
	v_mov_b32_e32 v57, v2
	v_mov_b32_e32 v62, v2
	v_mov_b32_e32 v63, v2
	v_mov_b32_e32 v64, v2
	v_mov_b32_e32 v65, v2
	v_mov_b32_e32 v66, v2
	v_mov_b32_e32 v67, v2
	v_mov_b32_e32 v68, v2
	v_mov_b32_e32 v69, v2
	v_mov_b32_e32 v74, v2
	v_mov_b32_e32 v75, v2
	v_mov_b32_e32 v76, v2
	v_mov_b32_e32 v77, v2
	v_mov_b32_e32 v90, v2
	v_mov_b32_e32 v91, v2
	v_mov_b32_e32 v92, v2
	v_mov_b32_e32 v93, v2
	v_mov_b32_e32 v106, v2
	v_mov_b32_e32 v107, v2
	v_mov_b32_e32 v108, v2
	v_mov_b32_e32 v109, v2
	v_mov_b32_e32 v114, v2
	v_mov_b32_e32 v115, v2
	v_mov_b32_e32 v116, v2
	v_mov_b32_e32 v117, v2
	v_mov_b32_e32 v122, v2
	v_mov_b32_e32 v123, v2
	v_mov_b32_e32 v124, v2
	v_mov_b32_e32 v125, v2
	v_mov_b32_e32 v130, v2
	v_mov_b32_e32 v131, v2
	v_mov_b32_e32 v132, v2
	v_mov_b32_e32 v133, v2
	v_mov_b32_e32 v142, v2
	v_mov_b32_e32 v143, v2
	v_mov_b32_e32 v144, v2
	v_mov_b32_e32 v145, v2
	v_mov_b32_e32 v70, v2
	v_mov_b32_e32 v71, v2
	v_mov_b32_e32 v72, v2
	v_mov_b32_e32 v73, v2
	v_mov_b32_e32 v78, v2
	v_mov_b32_e32 v79, v2
	v_mov_b32_e32 v80, v2
	v_mov_b32_e32 v81, v2
	v_mov_b32_e32 v98, v2
	v_mov_b32_e32 v99, v2
	v_mov_b32_e32 v100, v2
	v_mov_b32_e32 v101, v2
	v_mov_b32_e32 v110, v2
	v_mov_b32_e32 v111, v2
	v_mov_b32_e32 v112, v2
	v_mov_b32_e32 v113, v2
	v_mov_b32_e32 v118, v2
	v_mov_b32_e32 v119, v2
	v_mov_b32_e32 v120, v2
	v_mov_b32_e32 v121, v2
	v_mov_b32_e32 v126, v2
	v_mov_b32_e32 v127, v2
	v_mov_b32_e32 v128, v2
	v_mov_b32_e32 v129, v2
	v_mov_b32_e32 v138, v2
	v_mov_b32_e32 v139, v2
	v_mov_b32_e32 v140, v2
	v_mov_b32_e32 v141, v2
	v_mov_b32_e32 v146, v2
	v_mov_b32_e32 v147, v2
	v_mov_b32_e32 v148, v2
	v_mov_b32_e32 v149, v2
	.p2alignl 6, 3212836864

.LBB0_444:
	s_ashr_i32 s13, s12, 31
	s_lshl_b64 s[14:15], s[12:13], 19
	s_add_u32 s14, s29, s14
	s_addc_u32 s15, s30, s15
	s_and_b64 s[16:17], s[0:1], exec
	s_cselect_b32 s13, s15, s21
	s_cselect_b32 s66, s14, s20
	s_ashr_i32 s11, s10, 31
	s_lshl_b64 s[16:17], s[10:11], 19
	s_add_u32 s16, s31, s16
	s_addc_u32 s17, s34, s17
	s_and_b64 s[24:25], s[0:1], exec
	s_cselect_b32 s11, s17, s23
	s_cselect_b32 s67, s16, s22
	s_add_u32 s20, s20, 0x40080
	s_addc_u32 s21, s21, 0
	s_add_u32 s68, s22, 0x100
	v_mov_b32_e32 v2, 0
	s_addc_u32 s69, s23, 0
	s_mov_b32 s70, -2
	v_mov_b32_e32 v3, v2
	v_mov_b32_e32 v4, v2
	v_mov_b32_e32 v5, v2
	v_mov_b32_e32 v6, v2
	v_mov_b32_e32 v7, v2
	v_mov_b32_e32 v8, v2
	v_mov_b32_e32 v9, v2
	s_waitcnt vmcnt(0)
	v_mov_b32_e32 v18, v2
	v_mov_b32_e32 v19, v2
	v_mov_b32_e32 v20, v2
	v_mov_b32_e32 v21, v2
	v_mov_b32_e32 v22, v2
	v_mov_b32_e32 v23, v2
	v_mov_b32_e32 v24, v2
	v_mov_b32_e32 v25, v2
	v_mov_b32_e32 v34, v2
	v_mov_b32_e32 v35, v2
	v_mov_b32_e32 v36, v2
	v_mov_b32_e32 v37, v2
	v_mov_b32_e32 v38, v2
	v_mov_b32_e32 v39, v2
	v_mov_b32_e32 v40, v2
	v_mov_b32_e32 v41, v2
	v_mov_b32_e32 v50, v2
	v_mov_b32_e32 v51, v2
	v_mov_b32_e32 v52, v2
	v_mov_b32_e32 v53, v2
	v_mov_b32_e32 v54, v2
	v_mov_b32_e32 v55, v2
	v_mov_b32_e32 v56, v2
	v_mov_b32_e32 v57, v2
	v_mov_b32_e32 v10, v2
	v_mov_b32_e32 v11, v2
	v_mov_b32_e32 v12, v2
	v_mov_b32_e32 v13, v2
	v_mov_b32_e32 v14, v2
	v_mov_b32_e32 v15, v2
	v_mov_b32_e32 v16, v2
	v_mov_b32_e32 v17, v2
	v_mov_b32_e32 v26, v2
	v_mov_b32_e32 v27, v2
	v_mov_b32_e32 v28, v2
	v_mov_b32_e32 v29, v2
	v_mov_b32_e32 v30, v2
	v_mov_b32_e32 v31, v2
	v_mov_b32_e32 v32, v2
	v_mov_b32_e32 v33, v2
	v_mov_b32_e32 v42, v2
	v_mov_b32_e32 v43, v2
	v_mov_b32_e32 v44, v2
	v_mov_b32_e32 v45, v2
	v_mov_b32_e32 v46, v2
	v_mov_b32_e32 v47, v2
	v_mov_b32_e32 v48, v2
	v_mov_b32_e32 v49, v2
	v_mov_b32_e32 v58, v2
	v_mov_b32_e32 v59, v2
	v_mov_b32_e32 v60, v2
	v_mov_b32_e32 v61, v2
	v_mov_b32_e32 v62, v2
	v_mov_b32_e32 v63, v2
	v_mov_b32_e32 v64, v2
	v_mov_b32_e32 v65, v2
	v_mov_b32_e32 v66, v2
	v_mov_b32_e32 v67, v2
	v_mov_b32_e32 v68, v2
	v_mov_b32_e32 v69, v2
	v_mov_b32_e32 v70, v2
	v_mov_b32_e32 v71, v2
	v_mov_b32_e32 v72, v2
	v_mov_b32_e32 v73, v2
	v_mov_b32_e32 v82, v2
	v_mov_b32_e32 v83, v2
	v_mov_b32_e32 v84, v2
	v_mov_b32_e32 v85, v2
	v_mov_b32_e32 v86, v2
	v_mov_b32_e32 v87, v2
	v_mov_b32_e32 v88, v2
	v_mov_b32_e32 v89, v2
	v_mov_b32_e32 v98, v2
	v_mov_b32_e32 v99, v2
	v_mov_b32_e32 v100, v2
	v_mov_b32_e32 v101, v2
	v_mov_b32_e32 v102, v2
	v_mov_b32_e32 v103, v2
	v_mov_b32_e32 v104, v2
	v_mov_b32_e32 v105, v2
	v_mov_b32_e32 v114, v2
	v_mov_b32_e32 v115, v2
	v_mov_b32_e32 v116, v2
	v_mov_b32_e32 v117, v2
	v_mov_b32_e32 v118, v2
	v_mov_b32_e32 v119, v2
	v_mov_b32_e32 v120, v2
	v_mov_b32_e32 v121, v2
	v_mov_b32_e32 v74, v2
	v_mov_b32_e32 v75, v2
	v_mov_b32_e32 v76, v2
	v_mov_b32_e32 v77, v2
	v_mov_b32_e32 v78, v2
	v_mov_b32_e32 v79, v2
	v_mov_b32_e32 v80, v2
	v_mov_b32_e32 v81, v2
	v_mov_b32_e32 v90, v2
	v_mov_b32_e32 v91, v2
	v_mov_b32_e32 v92, v2
	v_mov_b32_e32 v93, v2
	v_mov_b32_e32 v94, v2
	v_mov_b32_e32 v95, v2
	v_mov_b32_e32 v96, v2
	v_mov_b32_e32 v97, v2
	v_mov_b32_e32 v106, v2
	v_mov_b32_e32 v107, v2
	v_mov_b32_e32 v108, v2
	v_mov_b32_e32 v109, v2
	v_mov_b32_e32 v110, v2
	v_mov_b32_e32 v111, v2
	v_mov_b32_e32 v112, v2
	v_mov_b32_e32 v113, v2
	v_mov_b32_e32 v122, v2
	v_mov_b32_e32 v123, v2
	v_mov_b32_e32 v124, v2
	v_mov_b32_e32 v125, v2
	v_mov_b32_e32 v126, v2
	v_mov_b32_e32 v127, v2
	v_mov_b32_e32 v128, v2
	v_mov_b32_e32 v129, v2
	.p2alignl 6, 3212836864

.LBB0_533:
	v_mov_b64_e32 v[2:3], 0x100
	s_ashr_i32 s13, s12, 31
	v_cmp_lt_i64_e32 vcc, s[14:15], v[2:3]
	s_lshl_b64 s[14:15], s[12:13], 21
	s_add_u32 s14, s31, s14
	s_addc_u32 s15, s34, s15
	s_and_b64 s[16:17], vcc, exec
	s_cselect_b32 s13, s15, s23
	s_cselect_b32 s19, s14, s22
	s_ashr_i32 s11, s10, 31
	s_lshl_b64 s[16:17], s[10:11], 21
	s_add_u32 s16, s35, s16
	s_addc_u32 s17, s36, s17
	s_and_b64 s[26:27], vcc, exec
	s_cselect_b32 s11, s17, s25
	s_cselect_b32 s21, s16, s24
	s_add_u32 s22, s22, 0x100080
	s_addc_u32 s23, s23, 0
	s_add_u32 s40, s24, 0x100
	v_mov_b32_e32 v2, 0
	s_addc_u32 s68, s25, 0
	s_mov_b32 s69, -2
	v_mov_b32_e32 v3, v2
	v_mov_b32_e32 v4, v2
	v_mov_b32_e32 v5, v2
	v_mov_b32_e32 v6, v2
	v_mov_b32_e32 v7, v2
	v_mov_b32_e32 v8, v2
	v_mov_b32_e32 v9, v2
	s_waitcnt vmcnt(0)
	v_mov_b32_e32 v18, v2
	v_mov_b32_e32 v19, v2
	v_mov_b32_e32 v20, v2
	v_mov_b32_e32 v21, v2
	v_mov_b32_e32 v22, v2
	v_mov_b32_e32 v23, v2
	v_mov_b32_e32 v24, v2
	v_mov_b32_e32 v25, v2
	v_mov_b32_e32 v34, v2
	v_mov_b32_e32 v35, v2
	v_mov_b32_e32 v36, v2
	v_mov_b32_e32 v37, v2
	v_mov_b32_e32 v38, v2
	v_mov_b32_e32 v39, v2
	v_mov_b32_e32 v40, v2
	v_mov_b32_e32 v41, v2
	v_mov_b32_e32 v50, v2
	v_mov_b32_e32 v51, v2
	v_mov_b32_e32 v52, v2
	v_mov_b32_e32 v53, v2
	v_mov_b32_e32 v54, v2
	v_mov_b32_e32 v55, v2
	v_mov_b32_e32 v56, v2
	v_mov_b32_e32 v57, v2
	v_mov_b32_e32 v10, v2
	v_mov_b32_e32 v11, v2
	v_mov_b32_e32 v12, v2
	v_mov_b32_e32 v13, v2
	v_mov_b32_e32 v14, v2
	v_mov_b32_e32 v15, v2
	v_mov_b32_e32 v16, v2
	v_mov_b32_e32 v17, v2
	v_mov_b32_e32 v26, v2
	v_mov_b32_e32 v27, v2
	v_mov_b32_e32 v28, v2
	v_mov_b32_e32 v29, v2
	v_mov_b32_e32 v30, v2
	v_mov_b32_e32 v31, v2
	v_mov_b32_e32 v32, v2
	v_mov_b32_e32 v33, v2
	v_mov_b32_e32 v42, v2
	v_mov_b32_e32 v43, v2
	v_mov_b32_e32 v44, v2
	v_mov_b32_e32 v45, v2
	v_mov_b32_e32 v46, v2
	v_mov_b32_e32 v47, v2
	v_mov_b32_e32 v48, v2
	v_mov_b32_e32 v49, v2
	v_mov_b32_e32 v58, v2
	v_mov_b32_e32 v59, v2
	v_mov_b32_e32 v60, v2
	v_mov_b32_e32 v61, v2
	v_mov_b32_e32 v62, v2
	v_mov_b32_e32 v63, v2
	v_mov_b32_e32 v64, v2
	v_mov_b32_e32 v65, v2
	v_mov_b32_e32 v66, v2
	v_mov_b32_e32 v67, v2
	v_mov_b32_e32 v68, v2
	v_mov_b32_e32 v69, v2
	v_mov_b32_e32 v70, v2
	v_mov_b32_e32 v71, v2
	v_mov_b32_e32 v72, v2
	v_mov_b32_e32 v73, v2
	v_mov_b32_e32 v82, v2
	v_mov_b32_e32 v83, v2
	v_mov_b32_e32 v84, v2
	v_mov_b32_e32 v85, v2
	v_mov_b32_e32 v86, v2
	v_mov_b32_e32 v87, v2
	v_mov_b32_e32 v88, v2
	v_mov_b32_e32 v89, v2
	v_mov_b32_e32 v98, v2
	v_mov_b32_e32 v99, v2
	v_mov_b32_e32 v100, v2
	v_mov_b32_e32 v101, v2
	v_mov_b32_e32 v102, v2
	v_mov_b32_e32 v103, v2
	v_mov_b32_e32 v104, v2
	v_mov_b32_e32 v105, v2
	v_mov_b32_e32 v114, v2
	v_mov_b32_e32 v115, v2
	v_mov_b32_e32 v116, v2
	v_mov_b32_e32 v117, v2
	v_mov_b32_e32 v118, v2
	v_mov_b32_e32 v119, v2
	v_mov_b32_e32 v120, v2
	v_mov_b32_e32 v121, v2
	v_mov_b32_e32 v74, v2
	v_mov_b32_e32 v75, v2
	v_mov_b32_e32 v76, v2
	v_mov_b32_e32 v77, v2
	v_mov_b32_e32 v78, v2
	v_mov_b32_e32 v79, v2
	v_mov_b32_e32 v80, v2
	v_mov_b32_e32 v81, v2
	v_mov_b32_e32 v90, v2
	v_mov_b32_e32 v91, v2
	v_mov_b32_e32 v92, v2
	v_mov_b32_e32 v93, v2
	v_mov_b32_e32 v94, v2
	v_mov_b32_e32 v95, v2
	v_mov_b32_e32 v96, v2
	v_mov_b32_e32 v97, v2
	v_mov_b32_e32 v106, v2
	v_mov_b32_e32 v107, v2
	v_mov_b32_e32 v108, v2
	v_mov_b32_e32 v109, v2
	v_mov_b32_e32 v110, v2
	v_mov_b32_e32 v111, v2
	v_mov_b32_e32 v112, v2
	v_mov_b32_e32 v113, v2
	v_mov_b32_e32 v122, v2
	v_mov_b32_e32 v123, v2
	v_mov_b32_e32 v124, v2
	v_mov_b32_e32 v125, v2
	v_mov_b32_e32 v126, v2
	v_mov_b32_e32 v127, v2
	v_mov_b32_e32 v128, v2
	v_mov_b32_e32 v129, v2
	.p2alignl 6, 3212836864

.LBB0_630:
	s_ashr_i32 s19, s18, 31
	s_lshl_b64 s[20:21], s[18:19], 19
	s_add_u32 s20, s39, s20
	s_addc_u32 s21, s42, s21
	s_and_b64 s[22:23], s[4:5], exec
	s_cselect_b32 s3, s21, s27
	s_cselect_b32 s19, s20, s26
	s_ashr_i32 s17, s16, 31
	s_lshl_b64 s[22:23], s[16:17], 19
	s_add_u32 s22, s43, s22
	s_addc_u32 s23, s44, s23
	s_and_b64 s[30:31], s[4:5], exec
	s_cselect_b32 s17, s23, s29
	s_cselect_b32 s58, s22, s28
	s_add_u32 s26, s26, 0x40080
	s_addc_u32 s27, s27, 0
	s_add_u32 s59, s28, 0x100
	v_mov_b32_e32 v2, 0
	s_addc_u32 s60, s29, 0
	s_mov_b32 s61, -2
	v_mov_b32_e32 v3, v2
	v_mov_b32_e32 v4, v2
	v_mov_b32_e32 v5, v2
	v_mov_b32_e32 v6, v2
	v_mov_b32_e32 v7, v2
	v_mov_b32_e32 v8, v2
	v_mov_b32_e32 v9, v2
	s_waitcnt vmcnt(0)
	v_mov_b32_e32 v18, v2
	v_mov_b32_e32 v19, v2
	v_mov_b32_e32 v20, v2
	v_mov_b32_e32 v21, v2
	v_mov_b32_e32 v22, v2
	v_mov_b32_e32 v23, v2
	v_mov_b32_e32 v24, v2
	v_mov_b32_e32 v25, v2
	v_mov_b32_e32 v34, v2
	v_mov_b32_e32 v35, v2
	v_mov_b32_e32 v36, v2
	v_mov_b32_e32 v37, v2
	v_mov_b32_e32 v38, v2
	v_mov_b32_e32 v39, v2
	v_mov_b32_e32 v40, v2
	v_mov_b32_e32 v41, v2
	v_mov_b32_e32 v50, v2
	v_mov_b32_e32 v51, v2
	v_mov_b32_e32 v52, v2
	v_mov_b32_e32 v53, v2
	v_mov_b32_e32 v54, v2
	v_mov_b32_e32 v55, v2
	v_mov_b32_e32 v56, v2
	v_mov_b32_e32 v57, v2
	v_mov_b32_e32 v10, v2
	v_mov_b32_e32 v11, v2
	v_mov_b32_e32 v12, v2
	v_mov_b32_e32 v13, v2
	v_mov_b32_e32 v14, v2
	v_mov_b32_e32 v15, v2
	v_mov_b32_e32 v16, v2
	v_mov_b32_e32 v17, v2
	v_mov_b32_e32 v26, v2
	v_mov_b32_e32 v27, v2
	v_mov_b32_e32 v28, v2
	v_mov_b32_e32 v29, v2
	v_mov_b32_e32 v30, v2
	v_mov_b32_e32 v31, v2
	v_mov_b32_e32 v32, v2
	v_mov_b32_e32 v33, v2
	v_mov_b32_e32 v42, v2
	v_mov_b32_e32 v43, v2
	v_mov_b32_e32 v44, v2
	v_mov_b32_e32 v45, v2
	v_mov_b32_e32 v46, v2
	v_mov_b32_e32 v47, v2
	v_mov_b32_e32 v48, v2
	v_mov_b32_e32 v49, v2
	v_mov_b32_e32 v58, v2
	v_mov_b32_e32 v59, v2
	v_mov_b32_e32 v60, v2
	v_mov_b32_e32 v61, v2
	v_mov_b32_e32 v62, v2
	v_mov_b32_e32 v63, v2
	v_mov_b32_e32 v64, v2
	v_mov_b32_e32 v65, v2
	v_mov_b32_e32 v66, v2
	v_mov_b32_e32 v67, v2
	v_mov_b32_e32 v68, v2
	v_mov_b32_e32 v69, v2
	v_mov_b32_e32 v70, v2
	v_mov_b32_e32 v71, v2
	v_mov_b32_e32 v72, v2
	v_mov_b32_e32 v73, v2
	v_mov_b32_e32 v82, v2
	v_mov_b32_e32 v83, v2
	v_mov_b32_e32 v84, v2
	v_mov_b32_e32 v85, v2
	v_mov_b32_e32 v86, v2
	v_mov_b32_e32 v87, v2
	v_mov_b32_e32 v88, v2
	v_mov_b32_e32 v89, v2
	v_mov_b32_e32 v98, v2
	v_mov_b32_e32 v99, v2
	v_mov_b32_e32 v100, v2
	v_mov_b32_e32 v101, v2
	v_mov_b32_e32 v102, v2
	v_mov_b32_e32 v103, v2
	v_mov_b32_e32 v104, v2
	v_mov_b32_e32 v105, v2
	v_mov_b32_e32 v114, v2
	v_mov_b32_e32 v115, v2
	v_mov_b32_e32 v116, v2
	v_mov_b32_e32 v117, v2
	v_mov_b32_e32 v118, v2
	v_mov_b32_e32 v119, v2
	v_mov_b32_e32 v120, v2
	v_mov_b32_e32 v121, v2
	v_mov_b32_e32 v74, v2
	v_mov_b32_e32 v75, v2
	v_mov_b32_e32 v76, v2
	v_mov_b32_e32 v77, v2
	v_mov_b32_e32 v78, v2
	v_mov_b32_e32 v79, v2
	v_mov_b32_e32 v80, v2
	v_mov_b32_e32 v81, v2
	v_mov_b32_e32 v90, v2
	v_mov_b32_e32 v91, v2
	v_mov_b32_e32 v92, v2
	v_mov_b32_e32 v93, v2
	v_mov_b32_e32 v94, v2
	v_mov_b32_e32 v95, v2
	v_mov_b32_e32 v96, v2
	v_mov_b32_e32 v97, v2
	v_mov_b32_e32 v106, v2
	v_mov_b32_e32 v107, v2
	v_mov_b32_e32 v108, v2
	v_mov_b32_e32 v109, v2
	v_mov_b32_e32 v110, v2
	v_mov_b32_e32 v111, v2
	v_mov_b32_e32 v112, v2
	v_mov_b32_e32 v113, v2
	v_mov_b32_e32 v122, v2
	v_mov_b32_e32 v123, v2
	v_mov_b32_e32 v124, v2
	v_mov_b32_e32 v125, v2
	v_mov_b32_e32 v126, v2
	v_mov_b32_e32 v127, v2
	v_mov_b32_e32 v128, v2
	v_mov_b32_e32 v129, v2
	.p2alignl 6, 3212836864

.LBB0_938:
	s_ashr_i32 s13, s12, 31
	v_cmp_lt_i64_e32 vcc, s[14:15], v[198:199]
	s_lshl_b64 s[14:15], s[12:13], 19
	s_add_u32 s14, s31, s14
	s_addc_u32 s15, s34, s15
	s_and_b64 s[16:17], vcc, exec
	s_cselect_b32 s13, s15, s23
	s_cselect_b32 s19, s14, s22
	s_ashr_i32 s11, s10, 31
	s_lshl_b64 s[16:17], s[10:11], 19
	s_add_u32 s16, s35, s16
	s_addc_u32 s17, s36, s17
	s_and_b64 s[26:27], vcc, exec
	s_cselect_b32 s11, s17, s25
	s_cselect_b32 s21, s16, s24
	s_add_u32 s22, s22, 0x40080
	s_addc_u32 s23, s23, 0
	s_add_u32 s49, s24, 0x100
	v_mov_b32_e32 v2, 0
	s_addc_u32 s50, s25, 0
	s_mov_b32 s51, -2
	s_waitcnt lgkmcnt(0)
	v_mov_b32_e32 v3, v2
	v_mov_b32_e32 v4, v2
	v_mov_b32_e32 v5, v2
	v_mov_b32_e32 v6, v2
	v_mov_b32_e32 v7, v2
	v_mov_b32_e32 v8, v2
	v_mov_b32_e32 v9, v2
	v_mov_b32_e32 v18, v2
	v_mov_b32_e32 v19, v2
	v_mov_b32_e32 v20, v2
	v_mov_b32_e32 v21, v2
	v_mov_b32_e32 v22, v2
	v_mov_b32_e32 v23, v2
	v_mov_b32_e32 v24, v2
	v_mov_b32_e32 v25, v2
	v_mov_b32_e32 v34, v2
	v_mov_b32_e32 v35, v2
	v_mov_b32_e32 v36, v2
	v_mov_b32_e32 v37, v2
	v_mov_b32_e32 v38, v2
	v_mov_b32_e32 v39, v2
	v_mov_b32_e32 v40, v2
	v_mov_b32_e32 v41, v2
	v_mov_b32_e32 v50, v2
	v_mov_b32_e32 v51, v2
	v_mov_b32_e32 v52, v2
	v_mov_b32_e32 v53, v2
	v_mov_b32_e32 v54, v2
	v_mov_b32_e32 v55, v2
	v_mov_b32_e32 v56, v2
	v_mov_b32_e32 v57, v2
	v_mov_b32_e32 v10, v2
	v_mov_b32_e32 v11, v2
	v_mov_b32_e32 v12, v2
	v_mov_b32_e32 v13, v2
	v_mov_b32_e32 v14, v2
	v_mov_b32_e32 v15, v2
	v_mov_b32_e32 v16, v2
	v_mov_b32_e32 v17, v2
	v_mov_b32_e32 v26, v2
	v_mov_b32_e32 v27, v2
	v_mov_b32_e32 v28, v2
	v_mov_b32_e32 v29, v2
	v_mov_b32_e32 v30, v2
	v_mov_b32_e32 v31, v2
	v_mov_b32_e32 v32, v2
	v_mov_b32_e32 v33, v2
	v_mov_b32_e32 v42, v2
	v_mov_b32_e32 v43, v2
	v_mov_b32_e32 v44, v2
	v_mov_b32_e32 v45, v2
	v_mov_b32_e32 v46, v2
	v_mov_b32_e32 v47, v2
	v_mov_b32_e32 v48, v2
	v_mov_b32_e32 v49, v2
	v_mov_b32_e32 v58, v2
	v_mov_b32_e32 v59, v2
	v_mov_b32_e32 v60, v2
	v_mov_b32_e32 v61, v2
	v_mov_b32_e32 v62, v2
	v_mov_b32_e32 v63, v2
	v_mov_b32_e32 v64, v2
	v_mov_b32_e32 v65, v2
	v_mov_b32_e32 v66, v2
	v_mov_b32_e32 v67, v2
	v_mov_b32_e32 v68, v2
	v_mov_b32_e32 v69, v2
	v_mov_b32_e32 v70, v2
	v_mov_b32_e32 v71, v2
	v_mov_b32_e32 v72, v2
	v_mov_b32_e32 v73, v2
	v_mov_b32_e32 v82, v2
	v_mov_b32_e32 v83, v2
	v_mov_b32_e32 v84, v2
	v_mov_b32_e32 v85, v2
	v_mov_b32_e32 v86, v2
	v_mov_b32_e32 v87, v2
	v_mov_b32_e32 v88, v2
	v_mov_b32_e32 v89, v2
	v_mov_b32_e32 v98, v2
	v_mov_b32_e32 v99, v2
	v_mov_b32_e32 v100, v2
	v_mov_b32_e32 v101, v2
	v_mov_b32_e32 v102, v2
	v_mov_b32_e32 v103, v2
	v_mov_b32_e32 v104, v2
	v_mov_b32_e32 v105, v2
	v_mov_b32_e32 v114, v2
	v_mov_b32_e32 v115, v2
	v_mov_b32_e32 v116, v2
	v_mov_b32_e32 v117, v2
	v_mov_b32_e32 v118, v2
	v_mov_b32_e32 v119, v2
	v_mov_b32_e32 v120, v2
	v_mov_b32_e32 v121, v2
	v_mov_b32_e32 v74, v2
	v_mov_b32_e32 v75, v2
	v_mov_b32_e32 v76, v2
	v_mov_b32_e32 v77, v2
	v_mov_b32_e32 v78, v2
	v_mov_b32_e32 v79, v2
	v_mov_b32_e32 v80, v2
	v_mov_b32_e32 v81, v2
	v_mov_b32_e32 v90, v2
	v_mov_b32_e32 v91, v2
	v_mov_b32_e32 v92, v2
	v_mov_b32_e32 v93, v2
	v_mov_b32_e32 v94, v2
	v_mov_b32_e32 v95, v2
	v_mov_b32_e32 v96, v2
	v_mov_b32_e32 v97, v2
	v_mov_b32_e32 v106, v2
	v_mov_b32_e32 v107, v2
	v_mov_b32_e32 v108, v2
	v_mov_b32_e32 v109, v2
	v_mov_b32_e32 v110, v2
	v_mov_b32_e32 v111, v2
	v_mov_b32_e32 v112, v2
	v_mov_b32_e32 v113, v2
	v_mov_b32_e32 v122, v2
	v_mov_b32_e32 v123, v2
	v_mov_b32_e32 v124, v2
	v_mov_b32_e32 v125, v2
	v_mov_b32_e32 v126, v2
	v_mov_b32_e32 v127, v2
	v_mov_b32_e32 v128, v2
	v_mov_b32_e32 v129, v2
	.p2alignl 6, 3212836864

.LBB0_1039:
	s_ashr_i32 s13, s12, 31
	s_lshl_b64 s[14:15], s[12:13], 19
	s_add_u32 s14, s30, s14
	s_addc_u32 s15, s31, s15
	s_and_b64 s[16:17], s[0:1], exec
	s_cselect_b32 s13, s15, s21
	s_cselect_b32 s46, s14, s20
	s_ashr_i32 s11, s10, 31
	s_lshl_b64 s[16:17], s[10:11], 19
	s_add_u32 s16, s34, s16
	s_addc_u32 s17, s35, s17
	s_and_b64 s[24:25], s[0:1], exec
	s_cselect_b32 s11, s17, s23
	s_cselect_b32 s47, s16, s22
	s_add_u32 s20, s20, 0x40080
	s_addc_u32 s21, s21, 0
	s_add_u32 s48, s22, 0x100
	v_mov_b32_e32 v2, 0
	s_addc_u32 s49, s23, 0
	s_mov_b32 s50, -2
	v_mov_b32_e32 v3, v2
	v_mov_b32_e32 v4, v2
	v_mov_b32_e32 v5, v2
	v_mov_b32_e32 v6, v2
	v_mov_b32_e32 v7, v2
	v_mov_b32_e32 v8, v2
	v_mov_b32_e32 v9, v2
	v_mov_b32_e32 v18, v2
	v_mov_b32_e32 v19, v2
	v_mov_b32_e32 v20, v2
	v_mov_b32_e32 v21, v2
	v_mov_b32_e32 v22, v2
	v_mov_b32_e32 v23, v2
	v_mov_b32_e32 v24, v2
	v_mov_b32_e32 v25, v2
	v_mov_b32_e32 v34, v2
	v_mov_b32_e32 v35, v2
	v_mov_b32_e32 v36, v2
	v_mov_b32_e32 v37, v2
	v_mov_b32_e32 v38, v2
	v_mov_b32_e32 v39, v2
	v_mov_b32_e32 v40, v2
	v_mov_b32_e32 v41, v2
	v_mov_b32_e32 v50, v2
	v_mov_b32_e32 v51, v2
	v_mov_b32_e32 v52, v2
	v_mov_b32_e32 v53, v2
	v_mov_b32_e32 v54, v2
	v_mov_b32_e32 v55, v2
	v_mov_b32_e32 v56, v2
	v_mov_b32_e32 v57, v2
	v_mov_b32_e32 v10, v2
	v_mov_b32_e32 v11, v2
	v_mov_b32_e32 v12, v2
	v_mov_b32_e32 v13, v2
	v_mov_b32_e32 v14, v2
	v_mov_b32_e32 v15, v2
	v_mov_b32_e32 v16, v2
	v_mov_b32_e32 v17, v2
	v_mov_b32_e32 v26, v2
	v_mov_b32_e32 v27, v2
	v_mov_b32_e32 v28, v2
	v_mov_b32_e32 v29, v2
	v_mov_b32_e32 v30, v2
	v_mov_b32_e32 v31, v2
	v_mov_b32_e32 v32, v2
	v_mov_b32_e32 v33, v2
	v_mov_b32_e32 v42, v2
	v_mov_b32_e32 v43, v2
	v_mov_b32_e32 v44, v2
	v_mov_b32_e32 v45, v2
	v_mov_b32_e32 v46, v2
	v_mov_b32_e32 v47, v2
	v_mov_b32_e32 v48, v2
	v_mov_b32_e32 v49, v2
	v_mov_b32_e32 v58, v2
	v_mov_b32_e32 v59, v2
	v_mov_b32_e32 v60, v2
	v_mov_b32_e32 v61, v2
	v_mov_b32_e32 v62, v2
	v_mov_b32_e32 v63, v2
	v_mov_b32_e32 v64, v2
	v_mov_b32_e32 v65, v2
	v_mov_b32_e32 v66, v2
	v_mov_b32_e32 v67, v2
	v_mov_b32_e32 v68, v2
	v_mov_b32_e32 v69, v2
	v_mov_b32_e32 v70, v2
	v_mov_b32_e32 v71, v2
	v_mov_b32_e32 v72, v2
	v_mov_b32_e32 v73, v2
	v_mov_b32_e32 v82, v2
	v_mov_b32_e32 v83, v2
	v_mov_b32_e32 v84, v2
	v_mov_b32_e32 v85, v2
	v_mov_b32_e32 v86, v2
	v_mov_b32_e32 v87, v2
	v_mov_b32_e32 v88, v2
	v_mov_b32_e32 v89, v2
	v_mov_b32_e32 v98, v2
	v_mov_b32_e32 v99, v2
	v_mov_b32_e32 v100, v2
	v_mov_b32_e32 v101, v2
	v_mov_b32_e32 v102, v2
	v_mov_b32_e32 v103, v2
	v_mov_b32_e32 v104, v2
	v_mov_b32_e32 v105, v2
	v_mov_b32_e32 v114, v2
	v_mov_b32_e32 v115, v2
	v_mov_b32_e32 v116, v2
	v_mov_b32_e32 v117, v2
	v_mov_b32_e32 v118, v2
	v_mov_b32_e32 v119, v2
	v_mov_b32_e32 v120, v2
	v_mov_b32_e32 v121, v2
	v_mov_b32_e32 v74, v2
	v_mov_b32_e32 v75, v2
	v_mov_b32_e32 v76, v2
	v_mov_b32_e32 v77, v2
	v_mov_b32_e32 v78, v2
	v_mov_b32_e32 v79, v2
	v_mov_b32_e32 v80, v2
	v_mov_b32_e32 v81, v2
	v_mov_b32_e32 v90, v2
	v_mov_b32_e32 v91, v2
	v_mov_b32_e32 v92, v2
	v_mov_b32_e32 v93, v2
	v_mov_b32_e32 v94, v2
	v_mov_b32_e32 v95, v2
	v_mov_b32_e32 v96, v2
	v_mov_b32_e32 v97, v2
	v_mov_b32_e32 v106, v2
	v_mov_b32_e32 v107, v2
	v_mov_b32_e32 v108, v2
	v_mov_b32_e32 v109, v2
	v_mov_b32_e32 v110, v2
	v_mov_b32_e32 v111, v2
	v_mov_b32_e32 v112, v2
	v_mov_b32_e32 v113, v2
	v_mov_b32_e32 v122, v2
	v_mov_b32_e32 v123, v2
	v_mov_b32_e32 v124, v2
	v_mov_b32_e32 v125, v2
	v_mov_b32_e32 v126, v2
	v_mov_b32_e32 v127, v2
	v_mov_b32_e32 v128, v2
	v_mov_b32_e32 v129, v2
	.p2alignl 6, 3212836864

.LBB0_1129:
	s_ashr_i32 s21, s20, 31
	v_cmp_lt_i64_e32 vcc, s[22:23], v[198:199]
	s_lshl_b64 s[22:23], s[20:21], 21
	s_add_u32 s22, s37, s22
	s_addc_u32 s23, s38, s23
	s_and_b64 s[24:25], vcc, exec
	s_cselect_b32 s7, s23, s27
	s_cselect_b32 s9, s22, s26
	s_ashr_i32 s19, s18, 31
	s_lshl_b64 s[24:25], s[18:19], 21
	s_add_u32 s24, s39, s24
	s_addc_u32 s25, s42, s25
	s_and_b64 s[30:31], vcc, exec
	s_cselect_b32 s19, s25, s29
	s_cselect_b32 s21, s24, s28
	s_add_u32 s26, s26, 0x100080
	s_addc_u32 s27, s27, 0
	s_add_u32 s53, s28, 0x100
	v_mov_b32_e32 v2, 0
	s_addc_u32 s54, s29, 0
	s_mov_b32 s55, -2
	s_waitcnt lgkmcnt(0)
	v_mov_b32_e32 v3, v2
	v_mov_b32_e32 v4, v2
	v_mov_b32_e32 v5, v2
	v_mov_b32_e32 v6, v2
	v_mov_b32_e32 v7, v2
	v_mov_b32_e32 v8, v2
	v_mov_b32_e32 v9, v2
	v_mov_b32_e32 v18, v2
	v_mov_b32_e32 v19, v2
	v_mov_b32_e32 v20, v2
	v_mov_b32_e32 v21, v2
	v_mov_b32_e32 v22, v2
	v_mov_b32_e32 v23, v2
	v_mov_b32_e32 v24, v2
	v_mov_b32_e32 v25, v2
	v_mov_b32_e32 v34, v2
	v_mov_b32_e32 v35, v2
	v_mov_b32_e32 v36, v2
	v_mov_b32_e32 v37, v2
	v_mov_b32_e32 v38, v2
	v_mov_b32_e32 v39, v2
	v_mov_b32_e32 v40, v2
	v_mov_b32_e32 v41, v2
	v_mov_b32_e32 v50, v2
	v_mov_b32_e32 v51, v2
	v_mov_b32_e32 v52, v2
	v_mov_b32_e32 v53, v2
	v_mov_b32_e32 v54, v2
	v_mov_b32_e32 v55, v2
	v_mov_b32_e32 v56, v2
	v_mov_b32_e32 v57, v2
	v_mov_b32_e32 v10, v2
	v_mov_b32_e32 v11, v2
	v_mov_b32_e32 v12, v2
	v_mov_b32_e32 v13, v2
	v_mov_b32_e32 v14, v2
	v_mov_b32_e32 v15, v2
	v_mov_b32_e32 v16, v2
	v_mov_b32_e32 v17, v2
	v_mov_b32_e32 v26, v2
	v_mov_b32_e32 v27, v2
	v_mov_b32_e32 v28, v2
	v_mov_b32_e32 v29, v2
	v_mov_b32_e32 v30, v2
	v_mov_b32_e32 v31, v2
	v_mov_b32_e32 v32, v2
	v_mov_b32_e32 v33, v2
	v_mov_b32_e32 v42, v2
	v_mov_b32_e32 v43, v2
	v_mov_b32_e32 v44, v2
	v_mov_b32_e32 v45, v2
	v_mov_b32_e32 v46, v2
	v_mov_b32_e32 v47, v2
	v_mov_b32_e32 v48, v2
	v_mov_b32_e32 v49, v2
	v_mov_b32_e32 v58, v2
	v_mov_b32_e32 v59, v2
	v_mov_b32_e32 v60, v2
	v_mov_b32_e32 v61, v2
	v_mov_b32_e32 v62, v2
	v_mov_b32_e32 v63, v2
	v_mov_b32_e32 v64, v2
	v_mov_b32_e32 v65, v2
	v_mov_b32_e32 v66, v2
	v_mov_b32_e32 v67, v2
	v_mov_b32_e32 v68, v2
	v_mov_b32_e32 v69, v2
	v_mov_b32_e32 v70, v2
	v_mov_b32_e32 v71, v2
	v_mov_b32_e32 v72, v2
	v_mov_b32_e32 v73, v2
	v_mov_b32_e32 v82, v2
	v_mov_b32_e32 v83, v2
	v_mov_b32_e32 v84, v2
	v_mov_b32_e32 v85, v2
	v_mov_b32_e32 v86, v2
	v_mov_b32_e32 v87, v2
	v_mov_b32_e32 v88, v2
	v_mov_b32_e32 v89, v2
	v_mov_b32_e32 v98, v2
	v_mov_b32_e32 v99, v2
	v_mov_b32_e32 v100, v2
	v_mov_b32_e32 v101, v2
	v_mov_b32_e32 v102, v2
	v_mov_b32_e32 v103, v2
	v_mov_b32_e32 v104, v2
	v_mov_b32_e32 v105, v2
	v_mov_b32_e32 v114, v2
	v_mov_b32_e32 v115, v2
	v_mov_b32_e32 v116, v2
	v_mov_b32_e32 v117, v2
	v_mov_b32_e32 v118, v2
	v_mov_b32_e32 v119, v2
	v_mov_b32_e32 v120, v2
	v_mov_b32_e32 v121, v2
	v_mov_b32_e32 v74, v2
	v_mov_b32_e32 v75, v2
	v_mov_b32_e32 v76, v2
	v_mov_b32_e32 v77, v2
	v_mov_b32_e32 v78, v2
	v_mov_b32_e32 v79, v2
	v_mov_b32_e32 v80, v2
	v_mov_b32_e32 v81, v2
	v_mov_b32_e32 v90, v2
	v_mov_b32_e32 v91, v2
	v_mov_b32_e32 v92, v2
	v_mov_b32_e32 v93, v2
	v_mov_b32_e32 v94, v2
	v_mov_b32_e32 v95, v2
	v_mov_b32_e32 v96, v2
	v_mov_b32_e32 v97, v2
	v_mov_b32_e32 v106, v2
	v_mov_b32_e32 v107, v2
	v_mov_b32_e32 v108, v2
	v_mov_b32_e32 v109, v2
	v_mov_b32_e32 v110, v2
	v_mov_b32_e32 v111, v2
	v_mov_b32_e32 v112, v2
	v_mov_b32_e32 v113, v2
	v_mov_b32_e32 v122, v2
	v_mov_b32_e32 v123, v2
	v_mov_b32_e32 v124, v2
	v_mov_b32_e32 v125, v2
	v_mov_b32_e32 v126, v2
	v_mov_b32_e32 v127, v2
	v_mov_b32_e32 v128, v2
	v_mov_b32_e32 v129, v2
	.p2alignl 6, 3212836864
